# rstd_prefetch rewrite applied to P7's copy as well (P3 + P7: one memory round trip each instead of six)
# speedup vs baseline: 1.0035x; 1.0018x over previous
; #define LAS __attribute__((address_space(3)))
; __device__ __forceinline__ void rstd_prefetch(const Frame& F, const float* PP, const float* PS) {
;     LAS int* PMT = (LAS int*)(F.lds + PMT_OFF); LAS float* RSL = (LAS float*)(F.lds + RSL_OFF);
;     for (int i = 0; i < RSL_SLOTS; ++i) { const int L = i * F.G + (int)blockIdx.x; const bool ok = (L < 1496) && (F.G % 8 == 0);
;         const int pm = ok ? unit_pm_n5632(L) : -1;
;         if (ok && F.tid < 256) RSL[i * 256 + F.tid] = pg8::row_rstd(PP, PS, pm * 256 + F.tid);
;         if (F.tid == 0) PMT[i] = pm; }
.LBB0_1675:
	s_cmpk_lt_i32 s2, 0x5d8
	s_cselect_b64 s[16:17], -1, 0
	s_add_u32 s12, s22, 0xfd80000
	s_addc_u32 s13, s23, 0
	s_add_u32 s14, s22, 0xfdc0000
	s_addc_u32 s15, s23, 0
	s_mov_b32 s3, s2
	s_mov_b32 s6, -1
	s_cmpk_lt_i32 s3, 0x5d8
	s_cbranch_scc0 .Lrs_p7_n0
	s_cmp_eq_u64 s[90:91], 0
	s_cbranch_scc1 .Lrs_p7_n0
	s_and_b32 s34, s3, 7
	s_mul_i32 s34, s34, 0xbb
	s_lshr_b32 s35, s3, 3
	s_add_i32 s34, s34, s35
	s_mul_hi_u32 s35, s34, 0x1745d18
	s_mul_i32 s19, s35, 0xb0
	s_sub_i32 s34, s34, s19
	s_lshl_b32 s35, s35, 3
	s_sub_i32 s19, 0x44, s35
	s_min_i32 s19, s19, 8
	s_sub_i32 s19, s19, 1
	s_and_b32 s34, s34, s19
	s_add_i32 s6, s35, s34
.Lrs_p7_n0:
	s_add_i32 s3, s3, s18
	s_mov_b32 s7, -1
	s_cmpk_lt_i32 s3, 0x5d8
	s_cbranch_scc0 .Lrs_p7_n1
	s_cmp_eq_u64 s[90:91], 0
	s_cbranch_scc1 .Lrs_p7_n1
	s_and_b32 s34, s3, 7
	s_mul_i32 s34, s34, 0xbb
	s_lshr_b32 s35, s3, 3
	s_add_i32 s34, s34, s35
	s_mul_hi_u32 s35, s34, 0x1745d18
	s_mul_i32 s19, s35, 0xb0
	s_sub_i32 s34, s34, s19
	s_lshl_b32 s35, s35, 3
	s_sub_i32 s19, 0x44, s35
	s_min_i32 s19, s19, 8
	s_sub_i32 s19, s19, 1
	s_and_b32 s34, s34, s19
	s_add_i32 s7, s35, s34
.Lrs_p7_n1:
	s_add_i32 s3, s3, s18
	s_mov_b32 s8, -1
	s_cmpk_lt_i32 s3, 0x5d8
	s_cbranch_scc0 .Lrs_p7_n2
	s_cmp_eq_u64 s[90:91], 0
	s_cbranch_scc1 .Lrs_p7_n2
	s_and_b32 s34, s3, 7
	s_mul_i32 s34, s34, 0xbb
	s_lshr_b32 s35, s3, 3
	s_add_i32 s34, s34, s35
	s_mul_hi_u32 s35, s34, 0x1745d18
	s_mul_i32 s19, s35, 0xb0
	s_sub_i32 s34, s34, s19
	s_lshl_b32 s35, s35, 3
	s_sub_i32 s19, 0x44, s35
	s_min_i32 s19, s19, 8
	s_sub_i32 s19, s19, 1
	s_and_b32 s34, s34, s19
	s_add_i32 s8, s35, s34
.Lrs_p7_n2:
	s_add_i32 s3, s3, s18
	s_mov_b32 s9, -1
	s_cmpk_lt_i32 s3, 0x5d8
	s_cbranch_scc0 .Lrs_p7_n3
	s_cmp_eq_u64 s[90:91], 0
	s_cbranch_scc1 .Lrs_p7_n3
	s_and_b32 s34, s3, 7
	s_mul_i32 s34, s34, 0xbb
	s_lshr_b32 s35, s3, 3
	s_add_i32 s34, s34, s35
	s_mul_hi_u32 s35, s34, 0x1745d18
	s_mul_i32 s19, s35, 0xb0
	s_sub_i32 s34, s34, s19
	s_lshl_b32 s35, s35, 3
	s_sub_i32 s19, 0x44, s35
	s_min_i32 s19, s19, 8
	s_sub_i32 s19, s19, 1
	s_and_b32 s34, s34, s19
	s_add_i32 s9, s35, s34
.Lrs_p7_n3:
	s_add_i32 s3, s3, s18
	s_mov_b32 s10, -1
	s_cmpk_lt_i32 s3, 0x5d8
	s_cbranch_scc0 .Lrs_p7_n4
	s_cmp_eq_u64 s[90:91], 0
	s_cbranch_scc1 .Lrs_p7_n4
	s_and_b32 s34, s3, 7
	s_mul_i32 s34, s34, 0xbb
	s_lshr_b32 s35, s3, 3
	s_add_i32 s34, s34, s35
	s_mul_hi_u32 s35, s34, 0x1745d18
	s_mul_i32 s19, s35, 0xb0
	s_sub_i32 s34, s34, s19
	s_lshl_b32 s35, s35, 3
	s_sub_i32 s19, 0x44, s35
	s_min_i32 s19, s19, 8
	s_sub_i32 s19, s19, 1
	s_and_b32 s34, s34, s19
	s_add_i32 s10, s35, s34
.Lrs_p7_n4:
	s_add_i32 s3, s3, s18
	s_mov_b32 s11, -1
	s_cmpk_lt_i32 s3, 0x5d8
	s_cbranch_scc0 .Lrs_p7_n5
	s_cmp_eq_u64 s[90:91], 0
	s_cbranch_scc1 .Lrs_p7_n5
	s_and_b32 s34, s3, 7
	s_mul_i32 s34, s34, 0xbb
	s_lshr_b32 s35, s3, 3
	s_add_i32 s34, s34, s35
	s_mul_hi_u32 s35, s34, 0x1745d18
	s_mul_i32 s19, s35, 0xb0
	s_sub_i32 s34, s34, s19
	s_lshl_b32 s35, s35, 3
	s_sub_i32 s19, 0x44, s35
	s_min_i32 s19, s19, 8
	s_sub_i32 s19, s19, 1
	s_and_b32 s34, s34, s19
	s_add_i32 s11, s35, s34
.Lrs_p7_n5:
	s_add_i32 s3, s3, s18
	v_cmp_gt_u32_e32 vcc, 0x100, v188
	s_and_saveexec_b64 s[36:37], vcc
	s_cbranch_execz .Lrs_p7_rows_done
	s_cmp_lt_i32 s6, 0
	s_cbranch_scc1 .Lrs_p7_l0
	s_cmp_lt_i32 s6, 64
	s_cbranch_scc0 .Lrs_p7_s0
	v_lshl_add_u32 v1, s6, 8, v188
	v_lshlrev_b32_e32 v1, 4, v1
	global_load_dwordx4 v[20:23], v1, s[12:13]
	s_branch .Lrs_p7_l0
.Lrs_p7_s0:
	s_sub_i32 s34, s6, 64
	v_lshl_add_u32 v1, s34, 8, v188
	v_lshlrev_b32_e32 v1, 6, v1
	global_load_dwordx4 v[20:23], v1, s[14:15]
	global_load_dwordx4 v[24:27], v1, s[14:15] offset:16
	global_load_dwordx4 v[28:31], v1, s[14:15] offset:32
	global_load_dwordx4 v[32:35], v1, s[14:15] offset:48
.Lrs_p7_l0:
	s_cmp_lt_i32 s7, 0
	s_cbranch_scc1 .Lrs_p7_l1
	s_cmp_lt_i32 s7, 64
	s_cbranch_scc0 .Lrs_p7_s1
	v_lshl_add_u32 v1, s7, 8, v188
	v_lshlrev_b32_e32 v1, 4, v1
	global_load_dwordx4 v[36:39], v1, s[12:13]
	s_branch .Lrs_p7_l1
.Lrs_p7_s1:
	s_sub_i32 s34, s7, 64
	v_lshl_add_u32 v1, s34, 8, v188
	v_lshlrev_b32_e32 v1, 6, v1
	global_load_dwordx4 v[36:39], v1, s[14:15]
	global_load_dwordx4 v[40:43], v1, s[14:15] offset:16
	global_load_dwordx4 v[44:47], v1, s[14:15] offset:32
	global_load_dwordx4 v[48:51], v1, s[14:15] offset:48
.Lrs_p7_l1:
	s_cmp_lt_i32 s8, 0
	s_cbranch_scc1 .Lrs_p7_l2
	s_cmp_lt_i32 s8, 64
	s_cbranch_scc0 .Lrs_p7_s2
	v_lshl_add_u32 v1, s8, 8, v188
	v_lshlrev_b32_e32 v1, 4, v1
	global_load_dwordx4 v[52:55], v1, s[12:13]
	s_branch .Lrs_p7_l2
.Lrs_p7_s2:
	s_sub_i32 s34, s8, 64
	v_lshl_add_u32 v1, s34, 8, v188
	v_lshlrev_b32_e32 v1, 6, v1
	global_load_dwordx4 v[52:55], v1, s[14:15]
	global_load_dwordx4 v[56:59], v1, s[14:15] offset:16
	global_load_dwordx4 v[60:63], v1, s[14:15] offset:32
	global_load_dwordx4 v[64:67], v1, s[14:15] offset:48
.Lrs_p7_l2:
	s_cmp_lt_i32 s9, 0
	s_cbranch_scc1 .Lrs_p7_l3
	s_cmp_lt_i32 s9, 64
	s_cbranch_scc0 .Lrs_p7_s3
	v_lshl_add_u32 v1, s9, 8, v188
	v_lshlrev_b32_e32 v1, 4, v1
	global_load_dwordx4 v[68:71], v1, s[12:13]
	s_branch .Lrs_p7_l3
.Lrs_p7_s3:
	s_sub_i32 s34, s9, 64
	v_lshl_add_u32 v1, s34, 8, v188
	v_lshlrev_b32_e32 v1, 6, v1
	global_load_dwordx4 v[68:71], v1, s[14:15]
	global_load_dwordx4 v[72:75], v1, s[14:15] offset:16
	global_load_dwordx4 v[76:79], v1, s[14:15] offset:32
	global_load_dwordx4 v[80:83], v1, s[14:15] offset:48
.Lrs_p7_l3:
	s_cmp_lt_i32 s10, 0
	s_cbranch_scc1 .Lrs_p7_l4
	s_cmp_lt_i32 s10, 64
	s_cbranch_scc0 .Lrs_p7_s4
	v_lshl_add_u32 v1, s10, 8, v188
	v_lshlrev_b32_e32 v1, 4, v1
	global_load_dwordx4 v[84:87], v1, s[12:13]
	s_branch .Lrs_p7_l4
.Lrs_p7_s4:
	s_sub_i32 s34, s10, 64
	v_lshl_add_u32 v1, s34, 8, v188
	v_lshlrev_b32_e32 v1, 6, v1
	global_load_dwordx4 v[84:87], v1, s[14:15]
	global_load_dwordx4 v[88:91], v1, s[14:15] offset:16
	global_load_dwordx4 v[92:95], v1, s[14:15] offset:32
	global_load_dwordx4 v[96:99], v1, s[14:15] offset:48
.Lrs_p7_l4:
	s_cmp_lt_i32 s11, 0
	s_cbranch_scc1 .Lrs_p7_l5
	s_cmp_lt_i32 s11, 64
	s_cbranch_scc0 .Lrs_p7_s5
	v_lshl_add_u32 v1, s11, 8, v188
	v_lshlrev_b32_e32 v1, 4, v1
	global_load_dwordx4 v[100:103], v1, s[12:13]
	s_branch .Lrs_p7_l5
.Lrs_p7_s5:
	s_sub_i32 s34, s11, 64
	v_lshl_add_u32 v1, s34, 8, v188
	v_lshlrev_b32_e32 v1, 6, v1
	global_load_dwordx4 v[100:103], v1, s[14:15]
	global_load_dwordx4 v[104:107], v1, s[14:15] offset:16
	global_load_dwordx4 v[108:111], v1, s[14:15] offset:32
	global_load_dwordx4 v[112:115], v1, s[14:15] offset:48

; __device__ __forceinline__ float row_rstd(const float* PP, const float* PS, int row) {
;     float ss;
;     if (row < TP) { const f32x4 a = NTL((const f32x4*)(PP + (size_t)row * 4)); ss = (a[0] + a[1]) + (a[2] + a[3]); }
;     else { const f32x4* p = (const f32x4*)(PS + (size_t)(row - TP) * 16); const f32x4 a = (NTL(p) + NTL(p + 1)) + (NTL(p + 2) + NTL(p + 3)); ss = (a[0] + a[1]) + (a[2] + a[3]); }
;     return 1.0f / sqrtf(ss * (1.0f / DM) + EPS);
; }
.Lrs_p7_r0:
	v_add_f32_e32 v2, v21, v20
	v_add_f32_e32 v3, v22, v23
	v_add_f32_e32 v1, v2, v3
	v_mov_b32_e32 v2, 0x358637bd
	v_fmac_f32_e32 v2, 0x3a800000, v1
	v_mul_f32_e32 v1, 0x4f800000, v2
	v_cmp_gt_f32_e32 vcc, s19, v2
	s_nop 1
	v_cndmask_b32_e32 v1, v2, v1, vcc
	v_sqrt_f32_e32 v2, v1
	s_nop 0
	v_add_u32_e32 v3, -1, v2
	v_fma_f32 v4, -v3, v2, v1
	v_cmp_ge_f32_e64 s[34:35], 0, v4
	v_add_u32_e32 v4, 1, v2
	s_nop 0
	v_cndmask_b32_e64 v3, v2, v3, s[34:35]
	v_fma_f32 v2, -v4, v2, v1
	v_cmp_lt_f32_e64 s[34:35], 0, v2
	s_nop 1
	v_cndmask_b32_e64 v2, v3, v4, s[34:35]
	v_mul_f32_e32 v3, 0x37800000, v2
	v_cndmask_b32_e32 v2, v2, v3, vcc
	v_mov_b32_e32 v3, 0x260
	v_cmp_class_f32_e32 vcc, v1, v3
	s_nop 1
	v_cndmask_b32_e32 v1, v2, v1, vcc
	v_div_scale_f32 v2, s[34:35], v1, v1, 1.0
	v_rcp_f32_e32 v3, v2
	s_nop 0
	v_fma_f32 v4, -v2, v3, 1.0
	v_fmac_f32_e32 v3, v4, v3
	v_div_scale_f32 v4, vcc, 1.0, v1, 1.0
	v_mul_f32_e32 v5, v4, v3
	v_fma_f32 v6, -v2, v5, v4
	v_fmac_f32_e32 v5, v6, v3
	v_fma_f32 v2, -v2, v5, v4
	v_div_fmas_f32 v2, v2, v3, v5
	v_div_fixup_f32 v1, v2, v1, 1.0
	v_lshl_add_u32 v2, v188, 2, 0
	v_add_u32_e32 v2, 0x21000, v2
	ds_write_b32 v2, v1

; __device__ __forceinline__ float row_rstd(const float* PP, const float* PS, int row) {
;     float ss;
;     if (row < TP) { const f32x4 a = NTL((const f32x4*)(PP + (size_t)row * 4)); ss = (a[0] + a[1]) + (a[2] + a[3]); }
;     else { const f32x4* p = (const f32x4*)(PS + (size_t)(row - TP) * 16); const f32x4 a = (NTL(p) + NTL(p + 1)) + (NTL(p + 2) + NTL(p + 3)); ss = (a[0] + a[1]) + (a[2] + a[3]); }
;     return 1.0f / sqrtf(ss * (1.0f / DM) + EPS);
; }
.Lrs_p7_r1:
	v_add_f32_e32 v2, v37, v36
	v_add_f32_e32 v3, v38, v39
	v_add_f32_e32 v1, v2, v3
	v_mov_b32_e32 v2, 0x358637bd
	v_fmac_f32_e32 v2, 0x3a800000, v1
	v_mul_f32_e32 v1, 0x4f800000, v2
	v_cmp_gt_f32_e32 vcc, s19, v2
	s_nop 1
	v_cndmask_b32_e32 v1, v2, v1, vcc
	v_sqrt_f32_e32 v2, v1
	s_nop 0
	v_add_u32_e32 v3, -1, v2
	v_fma_f32 v4, -v3, v2, v1
	v_cmp_ge_f32_e64 s[34:35], 0, v4
	v_add_u32_e32 v4, 1, v2
	s_nop 0
	v_cndmask_b32_e64 v3, v2, v3, s[34:35]
	v_fma_f32 v2, -v4, v2, v1
	v_cmp_lt_f32_e64 s[34:35], 0, v2
	s_nop 1
	v_cndmask_b32_e64 v2, v3, v4, s[34:35]
	v_mul_f32_e32 v3, 0x37800000, v2
	v_cndmask_b32_e32 v2, v2, v3, vcc
	v_mov_b32_e32 v3, 0x260
	v_cmp_class_f32_e32 vcc, v1, v3
	s_nop 1
	v_cndmask_b32_e32 v1, v2, v1, vcc
	v_div_scale_f32 v2, s[34:35], v1, v1, 1.0
	v_rcp_f32_e32 v3, v2
	s_nop 0
	v_fma_f32 v4, -v2, v3, 1.0
	v_fmac_f32_e32 v3, v4, v3
	v_div_scale_f32 v4, vcc, 1.0, v1, 1.0
	v_mul_f32_e32 v5, v4, v3
	v_fma_f32 v6, -v2, v5, v4
	v_fmac_f32_e32 v5, v6, v3
	v_fma_f32 v2, -v2, v5, v4
	v_div_fmas_f32 v2, v2, v3, v5
	v_div_fixup_f32 v1, v2, v1, 1.0
	v_lshl_add_u32 v2, v188, 2, 0
	v_add_u32_e32 v2, 0x21400, v2
	ds_write_b32 v2, v1

; __device__ __forceinline__ float row_rstd(const float* PP, const float* PS, int row) {
;     float ss;
;     if (row < TP) { const f32x4 a = NTL((const f32x4*)(PP + (size_t)row * 4)); ss = (a[0] + a[1]) + (a[2] + a[3]); }
;     else { const f32x4* p = (const f32x4*)(PS + (size_t)(row - TP) * 16); const f32x4 a = (NTL(p) + NTL(p + 1)) + (NTL(p + 2) + NTL(p + 3)); ss = (a[0] + a[1]) + (a[2] + a[3]); }
;     return 1.0f / sqrtf(ss * (1.0f / DM) + EPS);
; }
.Lrs_p7_r2:
	v_add_f32_e32 v2, v53, v52
	v_add_f32_e32 v3, v54, v55
	v_add_f32_e32 v1, v2, v3
	v_mov_b32_e32 v2, 0x358637bd
	v_fmac_f32_e32 v2, 0x3a800000, v1
	v_mul_f32_e32 v1, 0x4f800000, v2
	v_cmp_gt_f32_e32 vcc, s19, v2
	s_nop 1
	v_cndmask_b32_e32 v1, v2, v1, vcc
	v_sqrt_f32_e32 v2, v1
	s_nop 0
	v_add_u32_e32 v3, -1, v2
	v_fma_f32 v4, -v3, v2, v1
	v_cmp_ge_f32_e64 s[34:35], 0, v4
	v_add_u32_e32 v4, 1, v2
	s_nop 0
	v_cndmask_b32_e64 v3, v2, v3, s[34:35]
	v_fma_f32 v2, -v4, v2, v1
	v_cmp_lt_f32_e64 s[34:35], 0, v2
	s_nop 1
	v_cndmask_b32_e64 v2, v3, v4, s[34:35]
	v_mul_f32_e32 v3, 0x37800000, v2
	v_cndmask_b32_e32 v2, v2, v3, vcc
	v_mov_b32_e32 v3, 0x260
	v_cmp_class_f32_e32 vcc, v1, v3
	s_nop 1
	v_cndmask_b32_e32 v1, v2, v1, vcc
	v_div_scale_f32 v2, s[34:35], v1, v1, 1.0
	v_rcp_f32_e32 v3, v2
	s_nop 0
	v_fma_f32 v4, -v2, v3, 1.0
	v_fmac_f32_e32 v3, v4, v3
	v_div_scale_f32 v4, vcc, 1.0, v1, 1.0
	v_mul_f32_e32 v5, v4, v3
	v_fma_f32 v6, -v2, v5, v4
	v_fmac_f32_e32 v5, v6, v3
	v_fma_f32 v2, -v2, v5, v4
	v_div_fmas_f32 v2, v2, v3, v5
	v_div_fixup_f32 v1, v2, v1, 1.0
	v_lshl_add_u32 v2, v188, 2, 0
	v_add_u32_e32 v2, 0x21800, v2
	ds_write_b32 v2, v1

; __device__ __forceinline__ float row_rstd(const float* PP, const float* PS, int row) {
;     float ss;
;     if (row < TP) { const f32x4 a = NTL((const f32x4*)(PP + (size_t)row * 4)); ss = (a[0] + a[1]) + (a[2] + a[3]); }
;     else { const f32x4* p = (const f32x4*)(PS + (size_t)(row - TP) * 16); const f32x4 a = (NTL(p) + NTL(p + 1)) + (NTL(p + 2) + NTL(p + 3)); ss = (a[0] + a[1]) + (a[2] + a[3]); }
;     return 1.0f / sqrtf(ss * (1.0f / DM) + EPS);
; }
.Lrs_p7_r3:
	v_add_f32_e32 v2, v69, v68
	v_add_f32_e32 v3, v70, v71
	v_add_f32_e32 v1, v2, v3
	v_mov_b32_e32 v2, 0x358637bd
	v_fmac_f32_e32 v2, 0x3a800000, v1
	v_mul_f32_e32 v1, 0x4f800000, v2
	v_cmp_gt_f32_e32 vcc, s19, v2
	s_nop 1
	v_cndmask_b32_e32 v1, v2, v1, vcc
	v_sqrt_f32_e32 v2, v1
	s_nop 0
	v_add_u32_e32 v3, -1, v2
	v_fma_f32 v4, -v3, v2, v1
	v_cmp_ge_f32_e64 s[34:35], 0, v4
	v_add_u32_e32 v4, 1, v2
	s_nop 0
	v_cndmask_b32_e64 v3, v2, v3, s[34:35]
	v_fma_f32 v2, -v4, v2, v1
	v_cmp_lt_f32_e64 s[34:35], 0, v2
	s_nop 1
	v_cndmask_b32_e64 v2, v3, v4, s[34:35]
	v_mul_f32_e32 v3, 0x37800000, v2
	v_cndmask_b32_e32 v2, v2, v3, vcc
	v_mov_b32_e32 v3, 0x260
	v_cmp_class_f32_e32 vcc, v1, v3
	s_nop 1
	v_cndmask_b32_e32 v1, v2, v1, vcc
	v_div_scale_f32 v2, s[34:35], v1, v1, 1.0
	v_rcp_f32_e32 v3, v2
	s_nop 0
	v_fma_f32 v4, -v2, v3, 1.0
	v_fmac_f32_e32 v3, v4, v3
	v_div_scale_f32 v4, vcc, 1.0, v1, 1.0
	v_mul_f32_e32 v5, v4, v3
	v_fma_f32 v6, -v2, v5, v4
	v_fmac_f32_e32 v5, v6, v3
	v_fma_f32 v2, -v2, v5, v4
	v_div_fmas_f32 v2, v2, v3, v5
	v_div_fixup_f32 v1, v2, v1, 1.0
	v_lshl_add_u32 v2, v188, 2, 0
	v_add_u32_e32 v2, 0x21c00, v2
	ds_write_b32 v2, v1

; __device__ __forceinline__ float row_rstd(const float* PP, const float* PS, int row) {
;     float ss;
;     if (row < TP) { const f32x4 a = NTL((const f32x4*)(PP + (size_t)row * 4)); ss = (a[0] + a[1]) + (a[2] + a[3]); }
;     else { const f32x4* p = (const f32x4*)(PS + (size_t)(row - TP) * 16); const f32x4 a = (NTL(p) + NTL(p + 1)) + (NTL(p + 2) + NTL(p + 3)); ss = (a[0] + a[1]) + (a[2] + a[3]); }
;     return 1.0f / sqrtf(ss * (1.0f / DM) + EPS);
; }
.Lrs_p7_r4:
	v_add_f32_e32 v2, v85, v84
	v_add_f32_e32 v3, v86, v87
	v_add_f32_e32 v1, v2, v3
	v_mov_b32_e32 v2, 0x358637bd
	v_fmac_f32_e32 v2, 0x3a800000, v1
	v_mul_f32_e32 v1, 0x4f800000, v2
	v_cmp_gt_f32_e32 vcc, s19, v2
	s_nop 1
	v_cndmask_b32_e32 v1, v2, v1, vcc
	v_sqrt_f32_e32 v2, v1
	s_nop 0
	v_add_u32_e32 v3, -1, v2
	v_fma_f32 v4, -v3, v2, v1
	v_cmp_ge_f32_e64 s[34:35], 0, v4
	v_add_u32_e32 v4, 1, v2
	s_nop 0
	v_cndmask_b32_e64 v3, v2, v3, s[34:35]
	v_fma_f32 v2, -v4, v2, v1
	v_cmp_lt_f32_e64 s[34:35], 0, v2
	s_nop 1
	v_cndmask_b32_e64 v2, v3, v4, s[34:35]
	v_mul_f32_e32 v3, 0x37800000, v2
	v_cndmask_b32_e32 v2, v2, v3, vcc
	v_mov_b32_e32 v3, 0x260
	v_cmp_class_f32_e32 vcc, v1, v3
	s_nop 1
	v_cndmask_b32_e32 v1, v2, v1, vcc
	v_div_scale_f32 v2, s[34:35], v1, v1, 1.0
	v_rcp_f32_e32 v3, v2
	s_nop 0
	v_fma_f32 v4, -v2, v3, 1.0
	v_fmac_f32_e32 v3, v4, v3
	v_div_scale_f32 v4, vcc, 1.0, v1, 1.0
	v_mul_f32_e32 v5, v4, v3
	v_fma_f32 v6, -v2, v5, v4
	v_fmac_f32_e32 v5, v6, v3
	v_fma_f32 v2, -v2, v5, v4
	v_div_fmas_f32 v2, v2, v3, v5
	v_div_fixup_f32 v1, v2, v1, 1.0
	v_lshl_add_u32 v2, v188, 2, 0
	v_add_u32_e32 v2, 0x22000, v2
	ds_write_b32 v2, v1

; __device__ __forceinline__ float row_rstd(const float* PP, const float* PS, int row) {
;     float ss;
;     if (row < TP) { const f32x4 a = NTL((const f32x4*)(PP + (size_t)row * 4)); ss = (a[0] + a[1]) + (a[2] + a[3]); }
;     else { const f32x4* p = (const f32x4*)(PS + (size_t)(row - TP) * 16); const f32x4 a = (NTL(p) + NTL(p + 1)) + (NTL(p + 2) + NTL(p + 3)); ss = (a[0] + a[1]) + (a[2] + a[3]); }
;     return 1.0f / sqrtf(ss * (1.0f / DM) + EPS);
; }
; __device__ __forceinline__ void rstd_prefetch(const Frame& F, const float* PP, const float* PS) {
;     ...
;         if (ok && F.tid < 256) RSL[i * 256 + F.tid] = pg8::row_rstd(PP, PS, pm * 256 + F.tid);
;         if (F.tid == 0) PMT[i] = pm; }
;     __syncthreads();
; }
.Lrs_p7_r5:
	v_add_f32_e32 v2, v101, v100
	v_add_f32_e32 v3, v102, v103
	v_add_f32_e32 v1, v2, v3
	v_mov_b32_e32 v2, 0x358637bd
	v_fmac_f32_e32 v2, 0x3a800000, v1
	v_mul_f32_e32 v1, 0x4f800000, v2
	v_cmp_gt_f32_e32 vcc, s19, v2
	s_nop 1
	v_cndmask_b32_e32 v1, v2, v1, vcc
	v_sqrt_f32_e32 v2, v1
	s_nop 0
	v_add_u32_e32 v3, -1, v2
	v_fma_f32 v4, -v3, v2, v1
	v_cmp_ge_f32_e64 s[34:35], 0, v4
	v_add_u32_e32 v4, 1, v2
	s_nop 0
	v_cndmask_b32_e64 v3, v2, v3, s[34:35]
	v_fma_f32 v2, -v4, v2, v1
	v_cmp_lt_f32_e64 s[34:35], 0, v2
	s_nop 1
	v_cndmask_b32_e64 v2, v3, v4, s[34:35]
	v_mul_f32_e32 v3, 0x37800000, v2
	v_cndmask_b32_e32 v2, v2, v3, vcc
	v_mov_b32_e32 v3, 0x260
	v_cmp_class_f32_e32 vcc, v1, v3
	s_nop 1
	v_cndmask_b32_e32 v1, v2, v1, vcc
	v_div_scale_f32 v2, s[34:35], v1, v1, 1.0
	v_rcp_f32_e32 v3, v2
	s_nop 0
	v_fma_f32 v4, -v2, v3, 1.0
	v_fmac_f32_e32 v3, v4, v3
	v_div_scale_f32 v4, vcc, 1.0, v1, 1.0
	v_mul_f32_e32 v5, v4, v3
	v_fma_f32 v6, -v2, v5, v4
	v_fmac_f32_e32 v5, v6, v3
	v_fma_f32 v2, -v2, v5, v4
	v_div_fmas_f32 v2, v2, v3, v5
	v_div_fixup_f32 v1, v2, v1, 1.0
	v_lshl_add_u32 v2, v188, 2, 0
	v_add_u32_e32 v2, 0x22400, v2
	ds_write_b32 v2, v1
.Lrs_p7_c5:
.Lrs_p7_rows_done:
	s_or_b64 exec, exec, s[36:37]
	v_cmp_eq_u32_e32 vcc, 0, v188
	s_and_saveexec_b64 s[36:37], vcc
	v_mov_b32_e32 v1, 0x20c00
	v_mov_b32_e32 v2, s6
	ds_write_b32 v1, v2
	v_mov_b32_e32 v2, s7
	ds_write_b32 v1, v2 offset:4
	v_mov_b32_e32 v2, s8
	ds_write_b32 v1, v2 offset:8
	v_mov_b32_e32 v2, s9
	ds_write_b32 v1, v2 offset:12
	v_mov_b32_e32 v2, s10
	ds_write_b32 v1, v2 offset:16
	v_mov_b32_e32 v2, s11
	ds_write_b32 v1, v2 offset:20
	s_or_b64 exec, exec, s[36:37]
	v_cndmask_b32_e64 v1, 0, 1, s[16:17]
	v_cmp_ne_u32_e64 s[6:7], 1, v1
	s_andn2_b64 vcc, exec, s[16:17]
	v_readfirstlane_b32 s36, v0
	s_waitcnt lgkmcnt(0)
	s_barrier
	s_cbranch_vccnz .LBB0_1737
	s_ashr_i32 s3, s2, 31
	s_lshr_b32 s3, s3, 29
	s_add_i32 s3, s2, s3
	s_ashr_i32 s8, s3, 3
	s_and_b32 s3, s3, -8
	s_sub_i32 s3, s2, s3
	s_cmp_lt_i32 s3, 0
	s_movk_i32 s9, 0xbc
	s_cselect_b32 s9, s9, 0xbb
	s_mul_i32 s3, s3, s9
	s_add_i32 s3, s3, s8
	s_mul_hi_i32 s8, s3, 0x2e8ba2e9
	s_lshr_b32 s9, s8, 31
	s_ashr_i32 s8, s8, 5
	s_add_i32 s8, s8, s9
	s_lshl_b32 s10, s8, 3
	s_sub_i32 s9, 0x44, s10
	s_mulk_i32 s8, 0xb0
	s_min_u32 s11, s9, 8
	s_sub_i32 s3, s3, s8
	s_sext_i32_i16 s8, s3
	v_cvt_f32_ubyte0_e32 v2, s11
	v_cvt_f32_i32_e32 v1, s8
	v_rcp_iflag_f32_e32 v3, v2
	s_ashr_i32 s8, s8, 30
	s_or_b32 s16, s8, 1
	v_mul_f32_e32 v3, v1, v3
	v_trunc_f32_e32 v3, v3
	v_fma_f32 v1, -v3, v2, v1
	v_cvt_i32_f32_e32 v3, v3
	v_cmp_ge_f32_e64 s[8:9], |v1|, v2
	s_and_b64 s[8:9], s[8:9], exec
	s_cselect_b32 s8, s16, 0
	v_readfirstlane_b32 s9, v3
	s_add_i32 s8, s9, s8
	s_sext_i32_i16 s48, s8
	s_mul_i32 s8, s8, s11
	s_sub_i32 s3, s3, s8
	s_sext_i32_i16 s3, s3
	s_add_i32 s8, s10, s3
